# grid barrier poll loops: s_sleep 6 instead of s_sleep 1 between polls (less polling traffic while stragglers finish)
# speedup vs baseline: 1.0026x; 1.0026x over previous
.LBB0_16:
	s_sleep 6
	global_load_dword v2, v0, s[4:5] offset:32 sc1
	s_waitcnt vmcnt(0)
	v_and_b32_e32 v2, 0xffff0000, v2
	v_cmp_ne_u32_e32 vcc, v2, v1
	s_or_b64 s[8:9], vcc, s[8:9]
	s_andn2_b64 exec, exec, s[8:9]
	s_cbranch_execnz .LBB0_16

.LBB0_110:
	global_load_dword v15, v16, s[16:17] sc1
	global_load_dword v0, v16, s[18:19] sc1
	global_load_dword v1, v16, s[20:21] sc1
	global_load_dword v2, v16, s[22:23] sc1
	global_load_dword v3, v16, s[24:25] sc1
	global_load_dword v4, v16, s[26:27] sc1
	global_load_dword v5, v16, s[28:29] sc1
	global_load_dword v6, v16, s[30:31] sc1
	global_load_dword v7, v16, s[34:35] sc1
	global_load_dword v8, v16, s[36:37] sc1
	global_load_dword v9, v16, s[38:39] sc1
	global_load_dword v10, v16, s[40:41] sc1
	global_load_dword v11, v16, s[42:43] sc1
	global_load_dword v12, v16, s[44:45] sc1
	global_load_dword v13, v16, s[52:53] sc1
	global_load_dword v14, v16, s[56:57] sc1
	s_mov_b64 s[58:59], -1
	s_mov_b64 s[60:61], -1
	s_waitcnt vmcnt(14)
	v_add_u32_e32 v17, v0, v15
	s_waitcnt vmcnt(13)
	v_add_u32_e32 v17, v17, v1
	s_waitcnt vmcnt(12)
	v_add_u32_e32 v17, v17, v2
	s_waitcnt vmcnt(11)
	v_add_u32_e32 v17, v17, v3
	s_waitcnt vmcnt(10)
	v_add_u32_e32 v17, v17, v4
	s_waitcnt vmcnt(9)
	v_add_u32_e32 v17, v17, v5
	s_waitcnt vmcnt(8)
	v_add_u32_e32 v17, v17, v6
	s_waitcnt vmcnt(7)
	v_add_u32_e32 v17, v17, v7
	s_waitcnt vmcnt(6)
	v_add_u32_e32 v17, v17, v8
	s_waitcnt vmcnt(5)
	v_add_u32_e32 v17, v17, v9
	s_waitcnt vmcnt(4)
	v_add_u32_e32 v17, v17, v10
	s_waitcnt vmcnt(3)
	v_add_u32_e32 v17, v17, v11
	s_waitcnt vmcnt(2)
	v_add_u32_e32 v17, v17, v12
	s_waitcnt vmcnt(1)
	v_add_u32_e32 v17, v17, v13
	s_waitcnt vmcnt(0)
	v_add_u32_e32 v17, v17, v14
	v_cmp_eq_u32_e32 vcc, s3, v17
	s_cbranch_vccnz .LBB0_109
	s_and_b32 s58, s13, 0xff
	s_cmp_eq_u32 s58, 0
	s_mov_b64 s[58:59], -1
	s_mov_b64 s[62:63], -1
	s_sleep 6
	s_cbranch_scc1 .LBB0_114
	s_and_b64 vcc, exec, s[62:63]
	s_cbranch_vccz .LBB0_109

.LBB0_128:
	s_and_b32 s13, s3, 0xff
	s_mov_b64 s[28:29], -1
	s_cmp_lg_u32 s13, 0
	s_mov_b64 s[34:35], -1
	s_sleep 6
	s_cbranch_scc0 .LBB0_131
	s_and_b64 vcc, exec, s[34:35]
	s_cbranch_vccz .LBB0_127

.LBB0_145:
	s_and_b32 s13, s3, 0xff
	s_cmp_lg_u32 s13, 0
	s_mov_b64 s[30:31], -1
	s_sleep 6
	s_cbranch_scc0 .LBB0_148
	s_mov_b64 s[34:35], -1
	s_and_b64 vcc, exec, s[30:31]
	s_cbranch_vccz .LBB0_144

.LBB0_291:
	global_load_dword v15, v16, s[10:11] sc1
	global_load_dword v0, v16, s[16:17] sc1
	global_load_dword v1, v16, s[18:19] sc1
	global_load_dword v2, v16, s[20:21] sc1
	global_load_dword v3, v16, s[22:23] sc1
	global_load_dword v4, v16, s[24:25] sc1
	global_load_dword v5, v16, s[26:27] sc1
	global_load_dword v6, v16, s[28:29] sc1
	global_load_dword v7, v16, s[30:31] sc1
	global_load_dword v8, v16, s[34:35] sc1
	global_load_dword v9, v16, s[36:37] sc1
	global_load_dword v10, v16, s[38:39] sc1
	global_load_dword v11, v16, s[40:41] sc1
	global_load_dword v12, v16, s[44:45] sc1
	global_load_dword v13, v16, s[58:59] sc1
	global_load_dword v14, v16, s[70:71] sc1
	s_mov_b64 s[72:73], -1
	s_mov_b64 s[74:75], -1
	s_waitcnt vmcnt(14)
	v_add_u32_e32 v17, v0, v15
	s_waitcnt vmcnt(13)
	v_add_u32_e32 v17, v17, v1
	s_waitcnt vmcnt(12)
	v_add_u32_e32 v17, v17, v2
	s_waitcnt vmcnt(11)
	v_add_u32_e32 v17, v17, v3
	s_waitcnt vmcnt(10)
	v_add_u32_e32 v17, v17, v4
	s_waitcnt vmcnt(9)
	v_add_u32_e32 v17, v17, v5
	s_waitcnt vmcnt(8)
	v_add_u32_e32 v17, v17, v6
	s_waitcnt vmcnt(7)
	v_add_u32_e32 v17, v17, v7
	s_waitcnt vmcnt(6)
	v_add_u32_e32 v17, v17, v8
	s_waitcnt vmcnt(5)
	v_add_u32_e32 v17, v17, v9
	s_waitcnt vmcnt(4)
	v_add_u32_e32 v17, v17, v10
	s_waitcnt vmcnt(3)
	v_add_u32_e32 v17, v17, v11
	s_waitcnt vmcnt(2)
	v_add_u32_e32 v17, v17, v12
	s_waitcnt vmcnt(1)
	v_add_u32_e32 v17, v17, v13
	s_waitcnt vmcnt(0)
	v_add_u32_e32 v17, v17, v14
	v_cmp_eq_u32_e32 vcc, s60, v17
	s_cbranch_vccnz .LBB0_290
	s_and_b32 s62, s61, 0xff
	s_cmp_eq_u32 s62, 0
	s_mov_b64 s[76:77], -1
	s_sleep 6
	s_cbranch_scc1 .LBB0_295
	s_and_b64 vcc, exec, s[76:77]
	s_cbranch_vccz .LBB0_290

.LBB0_309:
	s_and_b32 s28, s34, 0xff
	s_mov_b64 s[26:27], -1
	s_cmp_lg_u32 s28, 0
	s_mov_b64 s[30:31], -1
	s_sleep 6
	s_cbranch_scc0 .LBB0_312
	s_and_b64 vcc, exec, s[30:31]
	s_cbranch_vccz .LBB0_308

.LBB0_326:
	s_and_b32 s26, s34, 0xff
	s_cmp_lg_u32 s26, 0
	s_mov_b64 s[28:29], -1
	s_sleep 6
	s_cbranch_scc0 .LBB0_329
	s_mov_b64 s[30:31], -1
	s_and_b64 vcc, exec, s[28:29]
	s_cbranch_vccz .LBB0_325

.LBB0_395:
	global_load_dword v15, v16, s[10:11] sc1
	global_load_dword v0, v16, s[16:17] sc1
	global_load_dword v1, v16, s[18:19] sc1
	global_load_dword v2, v16, s[20:21] sc1
	global_load_dword v3, v16, s[22:23] sc1
	global_load_dword v4, v16, s[24:25] sc1
	global_load_dword v5, v16, s[26:27] sc1
	global_load_dword v6, v16, s[28:29] sc1
	global_load_dword v7, v16, s[30:31] sc1
	global_load_dword v8, v16, s[34:35] sc1
	global_load_dword v9, v16, s[36:37] sc1
	global_load_dword v10, v16, s[38:39] sc1
	global_load_dword v11, v16, s[40:41] sc1
	global_load_dword v12, v16, s[44:45] sc1
	global_load_dword v13, v16, s[58:59] sc1
	global_load_dword v14, v16, s[72:73] sc1
	s_mov_b64 s[74:75], -1
	s_mov_b64 s[76:77], -1
	s_waitcnt vmcnt(14)
	v_add_u32_e32 v17, v0, v15
	s_waitcnt vmcnt(13)
	v_add_u32_e32 v17, v17, v1
	s_waitcnt vmcnt(12)
	v_add_u32_e32 v17, v17, v2
	s_waitcnt vmcnt(11)
	v_add_u32_e32 v17, v17, v3
	s_waitcnt vmcnt(10)
	v_add_u32_e32 v17, v17, v4
	s_waitcnt vmcnt(9)
	v_add_u32_e32 v17, v17, v5
	s_waitcnt vmcnt(8)
	v_add_u32_e32 v17, v17, v6
	s_waitcnt vmcnt(7)
	v_add_u32_e32 v17, v17, v7
	s_waitcnt vmcnt(6)
	v_add_u32_e32 v17, v17, v8
	s_waitcnt vmcnt(5)
	v_add_u32_e32 v17, v17, v9
	s_waitcnt vmcnt(4)
	v_add_u32_e32 v17, v17, v10
	s_waitcnt vmcnt(3)
	v_add_u32_e32 v17, v17, v11
	s_waitcnt vmcnt(2)
	v_add_u32_e32 v17, v17, v12
	s_waitcnt vmcnt(1)
	v_add_u32_e32 v17, v17, v13
	s_waitcnt vmcnt(0)
	v_add_u32_e32 v17, v17, v14
	v_cmp_eq_u32_e32 vcc, s60, v17
	s_cbranch_vccnz .LBB0_394
	s_and_b32 s62, s61, 0xff
	s_cmp_eq_u32 s62, 0
	s_mov_b64 s[78:79], -1
	s_sleep 6
	s_cbranch_scc1 .LBB0_399
	s_and_b64 vcc, exec, s[78:79]
	s_cbranch_vccz .LBB0_394

.LBB0_555:
	global_load_dword v15, v16, s[10:11] sc1
	global_load_dword v0, v16, s[14:15] sc1
	global_load_dword v1, v16, s[16:17] sc1
	global_load_dword v2, v16, s[18:19] sc1
	global_load_dword v3, v16, s[20:21] sc1
	global_load_dword v4, v16, s[22:23] sc1
	global_load_dword v5, v16, s[24:25] sc1
	global_load_dword v6, v16, s[26:27] sc1
	global_load_dword v7, v16, s[28:29] sc1
	global_load_dword v8, v16, s[30:31] sc1
	global_load_dword v9, v16, s[34:35] sc1
	global_load_dword v10, v16, s[36:37] sc1
	global_load_dword v11, v16, s[38:39] sc1
	global_load_dword v12, v16, s[40:41] sc1
	global_load_dword v13, v16, s[44:45] sc1
	global_load_dword v14, v16, s[74:75] sc1
	s_mov_b64 s[76:77], -1
	s_mov_b64 s[78:79], -1
	s_waitcnt vmcnt(14)
	v_add_u32_e32 v17, v0, v15
	s_waitcnt vmcnt(13)
	v_add_u32_e32 v17, v17, v1
	s_waitcnt vmcnt(12)
	v_add_u32_e32 v17, v17, v2
	s_waitcnt vmcnt(11)
	v_add_u32_e32 v17, v17, v3
	s_waitcnt vmcnt(10)
	v_add_u32_e32 v17, v17, v4
	s_waitcnt vmcnt(9)
	v_add_u32_e32 v17, v17, v5
	s_waitcnt vmcnt(8)
	v_add_u32_e32 v17, v17, v6
	s_waitcnt vmcnt(7)
	v_add_u32_e32 v17, v17, v7
	s_waitcnt vmcnt(6)
	v_add_u32_e32 v17, v17, v8
	s_waitcnt vmcnt(5)
	v_add_u32_e32 v17, v17, v9
	s_waitcnt vmcnt(4)
	v_add_u32_e32 v17, v17, v10
	s_waitcnt vmcnt(3)
	v_add_u32_e32 v17, v17, v11
	s_waitcnt vmcnt(2)
	v_add_u32_e32 v17, v17, v12
	s_waitcnt vmcnt(1)
	v_add_u32_e32 v17, v17, v13
	s_waitcnt vmcnt(0)
	v_add_u32_e32 v17, v17, v14
	v_cmp_eq_u32_e32 vcc, s13, v17
	s_cbranch_vccnz .LBB0_554
	s_and_b32 s61, s60, 0xff
	s_cmp_eq_u32 s61, 0
	s_mov_b64 s[80:81], -1
	s_sleep 6
	s_cbranch_scc1 .LBB0_559
	s_and_b64 vcc, exec, s[80:81]
	s_cbranch_vccz .LBB0_554

.LBB0_573:
	s_and_b32 s26, s13, 0xff
	s_mov_b64 s[24:25], -1
	s_cmp_lg_u32 s26, 0
	s_mov_b64 s[28:29], -1
	s_sleep 6
	s_cbranch_scc0 .LBB0_576
	s_and_b64 vcc, exec, s[28:29]
	s_cbranch_vccz .LBB0_572

.LBB0_590:
	s_and_b32 s24, s13, 0xff
	s_cmp_lg_u32 s24, 0
	s_mov_b64 s[26:27], -1
	s_sleep 6
	s_cbranch_scc0 .LBB0_593
	s_mov_b64 s[28:29], -1
	s_and_b64 vcc, exec, s[26:27]
	s_cbranch_vccz .LBB0_589

.LBB0_883:
	global_load_dword v15, v16, s[8:9] sc1
	global_load_dword v0, v16, s[10:11] sc1
	global_load_dword v1, v16, s[12:13] sc1
	global_load_dword v2, v16, s[14:15] sc1
	global_load_dword v3, v16, s[16:17] sc1
	global_load_dword v4, v16, s[18:19] sc1
	global_load_dword v5, v16, s[20:21] sc1
	global_load_dword v6, v16, s[22:23] sc1
	global_load_dword v7, v16, s[24:25] sc1
	global_load_dword v8, v16, s[26:27] sc1
	global_load_dword v9, v16, s[28:29] sc1
	global_load_dword v10, v16, s[30:31] sc1
	global_load_dword v11, v16, s[34:35] sc1
	global_load_dword v12, v16, s[36:37] sc1
	global_load_dword v13, v16, s[38:39] sc1
	global_load_dword v14, v16, s[40:41] sc1
	s_mov_b64 s[44:45], -1
	s_mov_b64 s[64:65], -1
	s_waitcnt vmcnt(14)
	v_add_u32_e32 v17, v0, v15
	s_waitcnt vmcnt(13)
	v_add_u32_e32 v17, v17, v1
	s_waitcnt vmcnt(12)
	v_add_u32_e32 v17, v17, v2
	s_waitcnt vmcnt(11)
	v_add_u32_e32 v17, v17, v3
	s_waitcnt vmcnt(10)
	v_add_u32_e32 v17, v17, v4
	s_waitcnt vmcnt(9)
	v_add_u32_e32 v17, v17, v5
	s_waitcnt vmcnt(8)
	v_add_u32_e32 v17, v17, v6
	s_waitcnt vmcnt(7)
	v_add_u32_e32 v17, v17, v7
	s_waitcnt vmcnt(6)
	v_add_u32_e32 v17, v17, v8
	s_waitcnt vmcnt(5)
	v_add_u32_e32 v17, v17, v9
	s_waitcnt vmcnt(4)
	v_add_u32_e32 v17, v17, v10
	s_waitcnt vmcnt(3)
	v_add_u32_e32 v17, v17, v11
	s_waitcnt vmcnt(2)
	v_add_u32_e32 v17, v17, v12
	s_waitcnt vmcnt(1)
	v_add_u32_e32 v17, v17, v13
	s_waitcnt vmcnt(0)
	v_add_u32_e32 v17, v17, v14
	v_cmp_eq_u32_e32 vcc, s60, v17
	s_cbranch_vccnz .LBB0_882
	s_and_b32 s44, s61, 0xff
	s_cmp_eq_u32 s44, 0
	s_mov_b64 s[44:45], -1
	s_mov_b64 s[66:67], -1
	s_sleep 6
	s_cbranch_scc1 .LBB0_887
	s_and_b64 vcc, exec, s[66:67]
	s_cbranch_vccz .LBB0_882

.LBB0_901:
	s_and_b32 s22, s26, 0xff
	s_mov_b64 s[20:21], -1
	s_cmp_lg_u32 s22, 0
	s_mov_b64 s[24:25], -1
	s_sleep 6
	s_cbranch_scc0 .LBB0_904
	s_and_b64 vcc, exec, s[24:25]
	s_cbranch_vccz .LBB0_900

.LBB0_918:
	s_and_b32 s20, s26, 0xff
	s_cmp_lg_u32 s20, 0
	s_mov_b64 s[22:23], -1
	s_sleep 6
	s_cbranch_scc0 .LBB0_921
	s_mov_b64 s[24:25], -1
	s_and_b64 vcc, exec, s[22:23]
	s_cbranch_vccz .LBB0_917

.LBB0_1010:
	global_load_dword v15, v16, s[14:15] sc1
	global_load_dword v0, v16, s[16:17] sc1
	global_load_dword v1, v16, s[18:19] sc1
	global_load_dword v2, v16, s[20:21] sc1
	global_load_dword v3, v16, s[22:23] sc1
	global_load_dword v4, v16, s[24:25] sc1
	global_load_dword v5, v16, s[26:27] sc1
	global_load_dword v6, v16, s[28:29] sc1
	global_load_dword v7, v16, s[30:31] sc1
	global_load_dword v8, v16, s[34:35] sc1
	global_load_dword v9, v16, s[36:37] sc1
	global_load_dword v10, v16, s[38:39] sc1
	global_load_dword v11, v16, s[40:41] sc1
	global_load_dword v12, v16, s[44:45] sc1
	global_load_dword v13, v16, s[64:65] sc1
	global_load_dword v14, v16, s[66:67] sc1
	s_mov_b64 s[68:69], -1
	s_mov_b64 s[70:71], -1
	s_waitcnt vmcnt(14)
	v_add_u32_e32 v17, v0, v15
	s_waitcnt vmcnt(13)
	v_add_u32_e32 v17, v17, v1
	s_waitcnt vmcnt(12)
	v_add_u32_e32 v17, v17, v2
	s_waitcnt vmcnt(11)
	v_add_u32_e32 v17, v17, v3
	s_waitcnt vmcnt(10)
	v_add_u32_e32 v17, v17, v4
	s_waitcnt vmcnt(9)
	v_add_u32_e32 v17, v17, v5
	s_waitcnt vmcnt(8)
	v_add_u32_e32 v17, v17, v6
	s_waitcnt vmcnt(7)
	v_add_u32_e32 v17, v17, v7
	s_waitcnt vmcnt(6)
	v_add_u32_e32 v17, v17, v8
	s_waitcnt vmcnt(5)
	v_add_u32_e32 v17, v17, v9
	s_waitcnt vmcnt(4)
	v_add_u32_e32 v17, v17, v10
	s_waitcnt vmcnt(3)
	v_add_u32_e32 v17, v17, v11
	s_waitcnt vmcnt(2)
	v_add_u32_e32 v17, v17, v12
	s_waitcnt vmcnt(1)
	v_add_u32_e32 v17, v17, v13
	s_waitcnt vmcnt(0)
	v_add_u32_e32 v17, v17, v14
	v_cmp_eq_u32_e32 vcc, s60, v17
	s_cbranch_vccnz .LBB0_1009
	s_and_b32 s62, s61, 0xff
	s_cmp_eq_u32 s62, 0
	s_mov_b64 s[72:73], -1
	s_sleep 6
	s_cbranch_scc1 .LBB0_1014
	s_and_b64 vcc, exec, s[72:73]
	s_cbranch_vccz .LBB0_1009

.LBB0_1188:
	global_load_dword v15, v16, s[10:11] sc1
	global_load_dword v0, v16, s[12:13] sc1
	global_load_dword v1, v16, s[14:15] sc1
	global_load_dword v2, v16, s[16:17] sc1
	global_load_dword v3, v16, s[18:19] sc1
	global_load_dword v4, v16, s[20:21] sc1
	global_load_dword v5, v16, s[22:23] sc1
	global_load_dword v6, v16, s[24:25] sc1
	global_load_dword v7, v16, s[26:27] sc1
	global_load_dword v8, v16, s[28:29] sc1
	global_load_dword v9, v16, s[30:31] sc1
	global_load_dword v10, v16, s[34:35] sc1
	global_load_dword v11, v16, s[36:37] sc1
	global_load_dword v12, v16, s[38:39] sc1
	global_load_dword v13, v16, s[40:41] sc1
	global_load_dword v14, v16, s[44:45] sc1
	s_mov_b64 s[60:61], -1
	s_mov_b64 s[62:63], -1
	s_waitcnt vmcnt(14)
	v_add_u32_e32 v17, v0, v15
	s_waitcnt vmcnt(13)
	v_add_u32_e32 v17, v17, v1
	s_waitcnt vmcnt(12)
	v_add_u32_e32 v17, v17, v2
	s_waitcnt vmcnt(11)
	v_add_u32_e32 v17, v17, v3
	s_waitcnt vmcnt(10)
	v_add_u32_e32 v17, v17, v4
	s_waitcnt vmcnt(9)
	v_add_u32_e32 v17, v17, v5
	s_waitcnt vmcnt(8)
	v_add_u32_e32 v17, v17, v6
	s_waitcnt vmcnt(7)
	v_add_u32_e32 v17, v17, v7
	s_waitcnt vmcnt(6)
	v_add_u32_e32 v17, v17, v8
	s_waitcnt vmcnt(5)
	v_add_u32_e32 v17, v17, v9
	s_waitcnt vmcnt(4)
	v_add_u32_e32 v17, v17, v10
	s_waitcnt vmcnt(3)
	v_add_u32_e32 v17, v17, v11
	s_waitcnt vmcnt(2)
	v_add_u32_e32 v17, v17, v12
	s_waitcnt vmcnt(1)
	v_add_u32_e32 v17, v17, v13
	s_waitcnt vmcnt(0)
	v_add_u32_e32 v17, v17, v14
	v_cmp_eq_u32_e32 vcc, s66, v17
	s_cbranch_vccnz .LBB0_1187
	s_and_b32 s60, s67, 0xff
	s_cmp_eq_u32 s60, 0
	s_mov_b64 s[60:61], -1
	s_mov_b64 s[64:65], -1
	s_sleep 6
	s_cbranch_scc1 .LBB0_1192
	s_and_b64 vcc, exec, s[64:65]
	s_cbranch_vccz .LBB0_1187

.LBB0_1206:
	s_and_b32 s24, s28, 0xff
	s_mov_b64 s[22:23], -1
	s_cmp_lg_u32 s24, 0
	s_mov_b64 s[26:27], -1
	s_sleep 6
	s_cbranch_scc0 .LBB0_1209
	s_and_b64 vcc, exec, s[26:27]
	s_cbranch_vccz .LBB0_1205

.LBB0_1223:
	s_and_b32 s22, s28, 0xff
	s_cmp_lg_u32 s22, 0
	s_mov_b64 s[24:25], -1
	s_sleep 6
	s_cbranch_scc0 .LBB0_1226
	s_mov_b64 s[26:27], -1
	s_and_b64 vcc, exec, s[24:25]
	s_cbranch_vccz .LBB0_1222

.LBB0_1292:
	global_load_dword v15, v16, s[10:11] sc1
	global_load_dword v0, v16, s[14:15] sc1
	global_load_dword v1, v16, s[16:17] sc1
	global_load_dword v2, v16, s[18:19] sc1
	global_load_dword v3, v16, s[20:21] sc1
	global_load_dword v4, v16, s[22:23] sc1
	global_load_dword v5, v16, s[24:25] sc1
	global_load_dword v6, v16, s[26:27] sc1
	global_load_dword v7, v16, s[28:29] sc1
	global_load_dword v8, v16, s[30:31] sc1
	global_load_dword v9, v16, s[34:35] sc1
	global_load_dword v10, v16, s[36:37] sc1
	global_load_dword v11, v16, s[38:39] sc1
	global_load_dword v12, v16, s[40:41] sc1
	global_load_dword v13, v16, s[42:43] sc1
	global_load_dword v14, v16, s[44:45] sc1
	s_mov_b64 s[56:57], -1
	s_mov_b64 s[60:61], -1
	s_waitcnt vmcnt(14)
	v_add_u32_e32 v17, v0, v15
	s_waitcnt vmcnt(13)
	v_add_u32_e32 v17, v17, v1
	s_waitcnt vmcnt(12)
	v_add_u32_e32 v17, v17, v2
	s_waitcnt vmcnt(11)
	v_add_u32_e32 v17, v17, v3
	s_waitcnt vmcnt(10)
	v_add_u32_e32 v17, v17, v4
	s_waitcnt vmcnt(9)
	v_add_u32_e32 v17, v17, v5
	s_waitcnt vmcnt(8)
	v_add_u32_e32 v17, v17, v6
	s_waitcnt vmcnt(7)
	v_add_u32_e32 v17, v17, v7
	s_waitcnt vmcnt(6)
	v_add_u32_e32 v17, v17, v8
	s_waitcnt vmcnt(5)
	v_add_u32_e32 v17, v17, v9
	s_waitcnt vmcnt(4)
	v_add_u32_e32 v17, v17, v10
	s_waitcnt vmcnt(3)
	v_add_u32_e32 v17, v17, v11
	s_waitcnt vmcnt(2)
	v_add_u32_e32 v17, v17, v12
	s_waitcnt vmcnt(1)
	v_add_u32_e32 v17, v17, v13
	s_waitcnt vmcnt(0)
	v_add_u32_e32 v17, v17, v14
	v_cmp_eq_u32_e32 vcc, s47, v17
	s_cbranch_vccnz .LBB0_1291
	s_and_b32 s56, s64, 0xff
	s_cmp_eq_u32 s56, 0
	s_mov_b64 s[56:57], -1
	s_mov_b64 s[62:63], -1
	s_sleep 6
	s_cbranch_scc1 .LBB0_1296
	s_and_b64 vcc, exec, s[62:63]
	s_cbranch_vccz .LBB0_1291

.LBB0_1310:
	s_and_b32 s26, s30, 0xff
	s_mov_b64 s[24:25], -1
	s_cmp_lg_u32 s26, 0
	s_mov_b64 s[28:29], -1
	s_sleep 6
	s_cbranch_scc0 .LBB0_1313
	s_and_b64 vcc, exec, s[28:29]
	s_cbranch_vccz .LBB0_1309

.LBB0_1327:
	s_and_b32 s24, s30, 0xff
	s_cmp_lg_u32 s24, 0
	s_mov_b64 s[26:27], -1
	s_sleep 6
	s_cbranch_scc0 .LBB0_1330
	s_mov_b64 s[28:29], -1
	s_and_b64 vcc, exec, s[26:27]
	s_cbranch_vccz .LBB0_1326
